# S2 epilogue: per-group counted waits also for the first residual batch (vmcnt 16/19/22/25)
# speedup vs baseline: 1.0040x; 1.0040x over previous
.LBB0_489:
	v_lshl_add_u32 v196, s40, 8, v205
	v_lshl_add_u32 v192, s41, 8, v207
	v_ashrrev_i32_e32 v193, 31, v192
	v_ashrrev_i32_e32 v197, 31, v196
	v_lshl_add_u64 v[194:195], v[192:193], 2, s[52:53]
	v_lshlrev_b64 v[128:129], 13, v[196:197]
	v_lshl_add_u64 v[128:129], v[194:195], 0, v[128:129]
	global_load_dwordx4 v[214:217], v[128:129], off
	global_load_dwordx4 v[218:221], v[128:129], off offset:16
	global_load_dwordx4 v[222:225], v[128:129], off offset:512
	global_load_dwordx4 v[226:229], v[128:129], off offset:528
	v_or_b32_e32 v202, 16, v196
	v_or_b32_e32 v200, 32, v196
	v_or_b32_e32 v198, 48, v196
	v_ashrrev_i32_e32 v203, 31, v202
	v_ashrrev_i32_e32 v201, 31, v200
	v_ashrrev_i32_e32 v199, 31, v198
	v_lshlrev_b64 v[128:129], 13, v[202:203]
	v_lshlrev_b64 v[130:131], 13, v[200:201]
	v_lshlrev_b64 v[132:133], 13, v[198:199]
	v_lshl_add_u64 v[128:129], v[194:195], 0, v[128:129]
	v_lshl_add_u64 v[130:131], v[194:195], 0, v[130:131]
	v_lshl_add_u64 v[132:133], v[194:195], 0, v[132:133]
	global_load_dwordx4 v[168:171], v[128:129], off offset:16
	global_load_dwordx4 v[172:175], v[128:129], off
	global_load_dwordx4 v[160:163], v[128:129], off offset:528
	global_load_dwordx4 v[164:167], v[128:129], off offset:512
	global_load_dwordx4 v[152:155], v[130:131], off offset:16
	global_load_dwordx4 v[156:159], v[130:131], off
	global_load_dwordx4 v[144:147], v[130:131], off offset:528
	global_load_dwordx4 v[148:151], v[130:131], off offset:512
	global_load_dwordx4 v[136:139], v[132:133], off offset:16
	global_load_dwordx4 v[140:143], v[132:133], off
	s_nop 0
	global_load_dwordx4 v[128:131], v[132:133], off offset:528
	s_nop 0
	global_load_dwordx4 v[132:135], v[132:133], off offset:512
	v_add_u32_e32 v250, 0x80, v196
	v_ashrrev_i32_e32 v251, 31, v250
	v_lshlrev_b64 v[250:251], 13, v[250:251]
	v_lshl_add_u64 v[250:251], v[194:195], 0, v[250:251]
	global_load_dwordx4 v[234:237], v[250:251], off
	global_load_dwordx4 v[238:241], v[250:251], off offset:16
	global_load_dwordx4 v[242:245], v[250:251], off offset:512
	global_load_dwordx4 v[246:249], v[250:251], off offset:528
	v_and_b32_e32 v212, 64, v211
	v_xor_b32_e32 v204, 16, v211
	v_add_u32_e32 v231, 64, v212
	v_xor_b32_e32 v230, 32, v211
	v_cmp_lt_i32_e32 vcc, v204, v231
	v_lshlrev_b64 v[212:213], 12, v[196:197]
	s_waitcnt vmcnt(16)
	v_pk_fma_f32 v[126:127], v[126:127], 0.5, v[216:217] op_sel_hi:[1,0,1]
	v_cndmask_b32_e32 v204, v211, v204, vcc
	v_cmp_lt_i32_e32 vcc, v230, v231
	v_pk_fma_f32 v[124:125], v[124:125], 0.5, v[214:215] op_sel_hi:[1,0,1]
	v_pk_fma_f32 v[122:123], v[122:123], 0.5, v[220:221] op_sel_hi:[1,0,1]
	v_pk_fma_f32 v[120:121], v[120:121], 0.5, v[218:219] op_sel_hi:[1,0,1]
	v_pk_fma_f32 v[118:119], v[118:119], 0.5, v[224:225] op_sel_hi:[1,0,1]
	v_pk_fma_f32 v[116:117], v[116:117], 0.5, v[222:223] op_sel_hi:[1,0,1]
	v_pk_fma_f32 v[214:215], v[114:115], 0.5, v[228:229] op_sel_hi:[1,0,1]
	v_pk_fma_f32 v[216:217], v[112:113], 0.5, v[226:227] op_sel_hi:[1,0,1]
	v_cndmask_b32_e32 v232, v211, v230, vcc
	v_lshl_add_u64 v[230:231], s[16:17], 0, v[212:213]
	v_lshlrev_b32_e32 v212, 2, v204
	v_cvt_pk_bf16_f32 v112, v124, v125
	v_cvt_pk_bf16_f32 v113, v126, v127
	v_cvt_pk_bf16_f32 v114, v120, v121
	v_mul_f32_e32 v115, v125, v125
	v_mul_f32_e32 v125, v127, v127
	v_mul_f32_e32 v121, v121, v121
	v_mul_f32_e32 v127, v123, v123
	v_mul_f32_e32 v204, v117, v117
	v_mul_f32_e32 v213, v119, v119
	v_mul_f32_e32 v218, v217, v217
	v_mul_f32_e32 v219, v215, v215
	v_fmac_f32_e32 v115, v124, v124
	v_fmac_f32_e32 v125, v126, v126
	v_fmac_f32_e32 v121, v120, v120
	v_fmac_f32_e32 v127, v122, v122
	v_fmac_f32_e32 v204, v116, v116
	v_fmac_f32_e32 v213, v118, v118
	v_fmac_f32_e32 v218, v216, v216
	v_fmac_f32_e32 v219, v214, v214
	v_add_f32_e32 v115, v115, v125
	v_add_f32_e32 v120, v121, v127
	v_add_f32_e32 v121, v204, v213
	v_add_f32_e32 v124, v218, v219
	v_add_f32_e32 v115, v115, v120
	v_add_f32_e32 v120, v121, v124
	v_add_f32_e32 v120, v115, v120
	ds_bpermute_b32 v121, v212, v120
	v_lshl_add_u64 v[230:231], v[192:193], 1, v[230:231]
	v_cvt_pk_bf16_f32 v115, v122, v123
	global_store_dwordx4 v[230:231], v[112:115], off
	v_cvt_pk_bf16_f32 v116, v116, v117
	v_cvt_pk_bf16_f32 v117, v118, v119
	v_cvt_pk_bf16_f32 v118, v216, v217
	v_cvt_pk_bf16_f32 v119, v214, v215
	global_store_dwordx4 v[230:231], v[116:119], off offset:256
	s_waitcnt lgkmcnt(0)
	v_add_f32_e32 v114, v120, v121
	v_lshlrev_b32_e32 v120, 2, v232
	ds_bpermute_b32 v115, v120, v114
	v_lshl_add_u64 v[112:113], v[196:197], 2, s[12:13]
	s_and_saveexec_b64 s[4:5], s[6:7]
	s_nop 0
	s_waitcnt lgkmcnt(0)
	v_add_f32_e32 v114, v114, v115
	global_atomic_add_f32 v[112:113], v114, off
.LBB0_491:
	s_or_b64 exec, exec, s[4:5]
	v_add_u32_e32 v250, 0x90, v196
	v_ashrrev_i32_e32 v251, 31, v250
	v_lshlrev_b64 v[250:251], 13, v[250:251]
	v_lshl_add_u64 v[250:251], v[194:195], 0, v[250:251]
	global_load_dwordx4 v[214:217], v[250:251], off offset:16
	global_load_dwordx4 v[218:221], v[250:251], off
	global_load_dwordx4 v[222:225], v[250:251], off offset:528
	global_load_dwordx4 v[226:229], v[250:251], off offset:512
	s_waitcnt vmcnt(19)
	v_pk_fma_f32 v[108:109], v[108:109], 0.5, v[172:173] op_sel_hi:[1,0,1]
	v_pk_fma_f32 v[110:111], v[110:111], 0.5, v[174:175] op_sel_hi:[1,0,1]
	v_pk_fma_f32 v[118:119], v[104:105], 0.5, v[168:169] op_sel_hi:[1,0,1]
	v_cvt_pk_bf16_f32 v104, v108, v109
	v_mul_f32_e32 v109, v109, v109
	v_fmac_f32_e32 v109, v108, v108
	v_mul_f32_e32 v108, v111, v111
	v_pk_fma_f32 v[116:117], v[106:107], 0.5, v[170:171] op_sel_hi:[1,0,1]
	v_fmac_f32_e32 v108, v110, v110
	v_cvt_pk_bf16_f32 v105, v110, v111
	v_add_f32_e32 v108, v109, v108
	v_mul_f32_e32 v109, v119, v119
	v_mul_f32_e32 v110, v117, v117
	v_fmac_f32_e32 v109, v118, v118
	v_fmac_f32_e32 v110, v116, v116
	v_pk_fma_f32 v[102:103], v[102:103], 0.5, v[166:167] op_sel_hi:[1,0,1]
	v_pk_fma_f32 v[100:101], v[100:101], 0.5, v[164:165] op_sel_hi:[1,0,1]
	v_add_f32_e32 v109, v109, v110
	v_pk_fma_f32 v[110:111], v[96:97], 0.5, v[160:161] op_sel_hi:[1,0,1]
	v_mul_f32_e32 v96, v101, v101
	v_mul_f32_e32 v97, v103, v103
	v_cvt_pk_bf16_f32 v106, v118, v119
	v_cvt_pk_bf16_f32 v107, v116, v117
	v_add_f32_e32 v116, v108, v109
	v_pk_fma_f32 v[108:109], v[98:99], 0.5, v[162:163] op_sel_hi:[1,0,1]
	v_fmac_f32_e32 v96, v100, v100
	v_fmac_f32_e32 v97, v102, v102
	v_add_f32_e32 v96, v96, v97
	v_mul_f32_e32 v97, v111, v111
	v_mul_f32_e32 v98, v109, v109
	v_fmac_f32_e32 v97, v110, v110
	v_fmac_f32_e32 v98, v108, v108
	v_add_f32_e32 v97, v97, v98
	v_add_f32_e32 v96, v96, v97
	v_add_f32_e32 v99, v116, v96
	ds_bpermute_b32 v116, v212, v99
	s_waitcnt lgkmcnt(0)
	v_lshlrev_b64 v[114:115], 12, v[202:203]
	v_lshl_add_u64 v[96:97], s[16:17], 0, v[114:115]
	v_lshl_add_u64 v[114:115], v[192:193], 1, v[96:97]
	global_store_dwordx4 v[114:115], v[104:107], off
	v_add_f32_e32 v96, v99, v116
	ds_bpermute_b32 v97, v120, v96
	v_cvt_pk_bf16_f32 v98, v100, v101
	v_cvt_pk_bf16_f32 v99, v102, v103
	v_cvt_pk_bf16_f32 v100, v110, v111
	v_cvt_pk_bf16_f32 v101, v108, v109
	global_store_dwordx4 v[114:115], v[98:101], off offset:256
	s_and_saveexec_b64 s[4:5], s[6:7]
	s_nop 0
	s_waitcnt lgkmcnt(0)
	v_add_f32_e32 v96, v96, v97
	global_atomic_add_f32 v[112:113], v96, off offset:64
.LBB0_493:
	s_or_b64 exec, exec, s[4:5]
	v_add_u32_e32 v250, 0xa0, v196
	v_ashrrev_i32_e32 v251, 31, v250
	v_lshlrev_b64 v[250:251], 13, v[250:251]
	v_lshl_add_u64 v[250:251], v[194:195], 0, v[250:251]
	global_load_dwordx4 v[160:163], v[250:251], off offset:16
	global_load_dwordx4 v[164:167], v[250:251], off
	global_load_dwordx4 v[168:171], v[250:251], off offset:528
	global_load_dwordx4 v[172:175], v[250:251], off offset:512
	s_waitcnt vmcnt(22)
	v_pk_fma_f32 v[92:93], v[92:93], 0.5, v[156:157] op_sel_hi:[1,0,1]
	v_pk_fma_f32 v[94:95], v[94:95], 0.5, v[158:159] op_sel_hi:[1,0,1]
	v_pk_fma_f32 v[100:101], v[88:89], 0.5, v[152:153] op_sel_hi:[1,0,1]
	v_cvt_pk_bf16_f32 v88, v92, v93
	v_mul_f32_e32 v93, v93, v93
	v_fmac_f32_e32 v93, v92, v92
	v_mul_f32_e32 v92, v95, v95
	v_pk_fma_f32 v[98:99], v[90:91], 0.5, v[154:155] op_sel_hi:[1,0,1]
	v_fmac_f32_e32 v92, v94, v94
	v_cvt_pk_bf16_f32 v89, v94, v95
	v_add_f32_e32 v92, v93, v92
	v_mul_f32_e32 v93, v101, v101
	v_mul_f32_e32 v94, v99, v99
	v_fmac_f32_e32 v93, v100, v100
	v_fmac_f32_e32 v94, v98, v98
	v_pk_fma_f32 v[86:87], v[86:87], 0.5, v[150:151] op_sel_hi:[1,0,1]
	v_pk_fma_f32 v[84:85], v[84:85], 0.5, v[148:149] op_sel_hi:[1,0,1]
	v_add_f32_e32 v93, v93, v94
	v_pk_fma_f32 v[94:95], v[80:81], 0.5, v[144:145] op_sel_hi:[1,0,1]
	v_mul_f32_e32 v80, v85, v85
	v_mul_f32_e32 v81, v87, v87
	v_cvt_pk_bf16_f32 v90, v100, v101
	v_cvt_pk_bf16_f32 v91, v98, v99
	v_add_f32_e32 v98, v92, v93
	v_pk_fma_f32 v[92:93], v[82:83], 0.5, v[146:147] op_sel_hi:[1,0,1]
	v_fmac_f32_e32 v80, v84, v84
	v_fmac_f32_e32 v81, v86, v86
	v_add_f32_e32 v80, v80, v81
	v_mul_f32_e32 v81, v95, v95
	v_mul_f32_e32 v82, v93, v93
	v_fmac_f32_e32 v81, v94, v94
	v_fmac_f32_e32 v82, v92, v92
	v_add_f32_e32 v81, v81, v82
	v_add_f32_e32 v80, v80, v81
	v_add_f32_e32 v83, v98, v80
	ds_bpermute_b32 v98, v212, v83
	s_waitcnt lgkmcnt(0)
	v_lshlrev_b64 v[96:97], 12, v[200:201]
	v_lshl_add_u64 v[80:81], s[16:17], 0, v[96:97]
	v_lshl_add_u64 v[96:97], v[192:193], 1, v[80:81]
	global_store_dwordx4 v[96:97], v[88:91], off
	v_add_f32_e32 v80, v83, v98
	ds_bpermute_b32 v81, v120, v80
	v_cvt_pk_bf16_f32 v82, v84, v85
	v_cvt_pk_bf16_f32 v83, v86, v87
	v_cvt_pk_bf16_f32 v84, v94, v95
	v_cvt_pk_bf16_f32 v85, v92, v93
	global_store_dwordx4 v[96:97], v[82:85], off offset:256
	s_and_saveexec_b64 s[4:5], s[6:7]
	s_nop 0
	s_waitcnt lgkmcnt(0)
	v_add_f32_e32 v80, v80, v81
	global_atomic_add_f32 v[112:113], v80, off offset:128
.LBB0_495:
	s_or_b64 exec, exec, s[4:5]
	v_add_u32_e32 v250, 0xb0, v196
	v_ashrrev_i32_e32 v251, 31, v250
	v_lshlrev_b64 v[250:251], 13, v[250:251]
	v_lshl_add_u64 v[250:251], v[194:195], 0, v[250:251]
	global_load_dwordx4 v[144:147], v[250:251], off offset:16
	global_load_dwordx4 v[148:151], v[250:251], off
	global_load_dwordx4 v[152:155], v[250:251], off offset:528
	global_load_dwordx4 v[156:159], v[250:251], off offset:512
	s_waitcnt vmcnt(25)
	v_pk_fma_f32 v[76:77], v[76:77], 0.5, v[140:141] op_sel_hi:[1,0,1]
	v_pk_fma_f32 v[78:79], v[78:79], 0.5, v[142:143] op_sel_hi:[1,0,1]
	v_pk_fma_f32 v[84:85], v[72:73], 0.5, v[136:137] op_sel_hi:[1,0,1]
	v_cvt_pk_bf16_f32 v72, v76, v77
	v_mul_f32_e32 v77, v77, v77
	v_fmac_f32_e32 v77, v76, v76
	v_mul_f32_e32 v76, v79, v79
	v_pk_fma_f32 v[82:83], v[74:75], 0.5, v[138:139] op_sel_hi:[1,0,1]
	v_fmac_f32_e32 v76, v78, v78
	v_cvt_pk_bf16_f32 v73, v78, v79
	v_add_f32_e32 v76, v77, v76
	v_mul_f32_e32 v77, v85, v85
	v_mul_f32_e32 v78, v83, v83
	v_fmac_f32_e32 v77, v84, v84
	v_fmac_f32_e32 v78, v82, v82
	v_pk_fma_f32 v[70:71], v[70:71], 0.5, v[134:135] op_sel_hi:[1,0,1]
	v_pk_fma_f32 v[68:69], v[68:69], 0.5, v[132:133] op_sel_hi:[1,0,1]
	v_add_f32_e32 v77, v77, v78
	v_pk_fma_f32 v[78:79], v[64:65], 0.5, v[128:129] op_sel_hi:[1,0,1]
	v_mul_f32_e32 v64, v69, v69
	v_mul_f32_e32 v65, v71, v71
	v_cvt_pk_bf16_f32 v74, v84, v85
	v_cvt_pk_bf16_f32 v75, v82, v83
	v_add_f32_e32 v82, v76, v77
	v_pk_fma_f32 v[76:77], v[66:67], 0.5, v[130:131] op_sel_hi:[1,0,1]
	v_fmac_f32_e32 v64, v68, v68
	v_fmac_f32_e32 v65, v70, v70
	v_add_f32_e32 v64, v64, v65
	v_mul_f32_e32 v65, v79, v79
	v_mul_f32_e32 v66, v77, v77
	v_fmac_f32_e32 v65, v78, v78
	v_fmac_f32_e32 v66, v76, v76
	v_add_f32_e32 v65, v65, v66
	v_add_f32_e32 v64, v64, v65
	v_add_f32_e32 v67, v82, v64
	ds_bpermute_b32 v82, v212, v67
	s_waitcnt lgkmcnt(0)
	v_lshlrev_b64 v[80:81], 12, v[198:199]
	v_lshl_add_u64 v[64:65], s[16:17], 0, v[80:81]
	v_lshl_add_u64 v[80:81], v[192:193], 1, v[64:65]
	global_store_dwordx4 v[80:81], v[72:75], off
	v_add_f32_e32 v64, v67, v82
	ds_bpermute_b32 v65, v120, v64
	v_cvt_pk_bf16_f32 v66, v68, v69
	v_cvt_pk_bf16_f32 v67, v70, v71
	v_cvt_pk_bf16_f32 v68, v78, v79
	v_cvt_pk_bf16_f32 v69, v76, v77
	global_store_dwordx4 v[80:81], v[66:69], off offset:256
	s_and_saveexec_b64 s[4:5], s[6:7]
	s_nop 0
	s_waitcnt lgkmcnt(0)
	v_add_f32_e32 v64, v64, v65
	global_atomic_add_f32 v[112:113], v64, off offset:192
